# dynamic sample-item queue: thread 0 fetches the next item index (atomic) one item ahead so the round trip overlaps the current item
# baseline (speedup 1.0000x reference)
; #define LAS __attribute__((address_space(3)))
; __device__ __forceinline__ int fresh_tid() { int t = threadIdx.x; asm volatile("" : "+v"(t)); return t; }
; __device__ __forceinline__ void phase_mixers(ParamsK p, int l, LAS unsigned char* lds) {
;     ...
;     unsigned* ctr = (unsigned*)(p->ws + WS_BAR) + 3584 + 64 * l;
;     LAS int* slot = (LAS int*)(lds + 65536);
;     for (;;) {
;         if (fresh_tid() == 0) slot[0] = (int)__hip_atomic_fetch_add(ctr, 1u, __ATOMIC_RELAXED, __HIP_MEMORY_SCOPE_AGENT);
.LBB0_654:
	s_load_dwordx2 s[6:7], s[0:1], 0xf8
	v_readlane_b32 s4, v252, 19
	v_readlane_b32 s5, v252, 20
	s_lshl_b32 s30, s4, 9
	s_lshl_b32 s8, s4, 13
	s_lshl_b64 s[4:5], s[94:95], 2
	s_waitcnt lgkmcnt(0)
	s_add_u32 s4, s6, s4
	s_addc_u32 s5, s7, s5
	s_add_u32 s10, s4, 0x35ac3c00
	s_addc_u32 s11, s5, 0
	s_add_u32 s12, s6, 0x14300000
	s_addc_u32 s13, s7, 0
	s_add_u32 s31, s6, 0x23ea0000
	v_readlane_b32 s84, v252, 21
	s_mov_b32 s9, s53
	s_addc_u32 s34, s7, 0
	v_readlane_b32 s94, v252, 26
	v_readlane_b32 s85, v252, 22
	v_readlane_b32 s50, v252, 4
	v_readlane_b32 s55, v252, 10
	s_movk_i32 s35, 0x7f
	s_movk_i32 s70, 0x100
	s_movk_i32 s95, 0x207f
	v_mov_b32_e32 v253, 1
	v_cmp_eq_u32_e32 vcc, 0, v176
	s_and_saveexec_b64 s[4:5], vcc
	s_cbranch_execz .Lq_pre_done
	global_atomic_add v253, v1, v253, s[10:11] sc0
.Lq_pre_done:
	s_or_b64 exec, exec, s[4:5]
	s_branch .LBB0_658

; __device__ __forceinline__ int fresh_tid() { int t = threadIdx.x; asm volatile("" : "+v"(t)); return t; }
; __device__ __forceinline__ void phase_mixers(ParamsK p, int l, LAS unsigned char* lds) {
;     ...
;     for (;;) {
;         if (fresh_tid() == 0) slot[0] = (int)__hip_atomic_fetch_add(ctr, 1u, __ATOMIC_RELAXED, __HIP_MEMORY_SCOPE_AGENT);
;         __syncthreads();
;         const int item = slot[0];
;         __syncthreads();
.LBB0_658:
	v_mov_b32_e32 v0, v176
	s_nop 0
	v_cmp_eq_u32_e32 vcc, 0, v0
	s_and_saveexec_b64 s[4:5], vcc
	s_cbranch_execz .LBB0_662
	s_waitcnt vmcnt(0)
	v_mov_b32_e32 v0, v253
	v_mov_b32_e32 v253, 1
	s_add_i32 s14, 0, 0x10000
	v_mov_b32_e32 v2, s14
	ds_write_b32 v2, v0
	global_atomic_add v253, v1, v253, s[10:11] sc0

; __global__ void __launch_bounds__(512) hybrid_fwd(Params p_unused) {
	.amdhsa_kernel _Z10hybrid_fwd6Params
		.amdhsa_group_segment_fixed_size 0
		.amdhsa_private_segment_fixed_size 0
		.amdhsa_kernarg_size 512
		.amdhsa_user_sgpr_count 2
		.amdhsa_user_sgpr_dispatch_ptr 0
		.amdhsa_user_sgpr_queue_ptr 0
		.amdhsa_user_sgpr_kernarg_segment_ptr 1
		.amdhsa_user_sgpr_dispatch_id 0
		.amdhsa_user_sgpr_kernarg_preload_length 0
		.amdhsa_user_sgpr_kernarg_preload_offset 0
		.amdhsa_user_sgpr_private_segment_size 0
		.amdhsa_uses_dynamic_stack 0
		.amdhsa_enable_private_segment 0
		.amdhsa_system_sgpr_workgroup_id_x 1
		.amdhsa_system_sgpr_workgroup_id_y 0
		.amdhsa_system_sgpr_workgroup_id_z 0
		.amdhsa_system_sgpr_workgroup_info 0
		.amdhsa_system_vgpr_workitem_id 2
		.amdhsa_next_free_vgpr 254
		.amdhsa_next_free_sgpr 100
		.amdhsa_accum_offset 256
		.amdhsa_reserve_vcc 1
		.amdhsa_float_round_mode_32 0
		.amdhsa_float_round_mode_16_64 0
		.amdhsa_float_denorm_mode_32 3
		.amdhsa_float_denorm_mode_16_64 3
		.amdhsa_dx10_clamp 1
		.amdhsa_ieee_mode 1
		.amdhsa_fp16_overflow 0
		.amdhsa_tg_split 0
		.amdhsa_exception_fp_ieee_invalid_op 0
		.amdhsa_exception_fp_denorm_src 0
		.amdhsa_exception_fp_ieee_div_zero 0
		.amdhsa_exception_fp_ieee_overflow 0
		.amdhsa_exception_fp_ieee_underflow 0
		.amdhsa_exception_fp_ieee_inexact 0
		.amdhsa_exception_int_div_zero 0
	.end_amdhsa_kernel

; __global__ void __launch_bounds__(512) hybrid_fwd(Params p_unused) {
amdhsa.kernels:
  - .agpr_count:     0
    .args:
      - .offset:         0
        .size:           256
        .value_kind:     by_value
      - .offset:         256
        .size:           4
        .value_kind:     hidden_block_count_x
      - .offset:         260
        .size:           4
        .value_kind:     hidden_block_count_y
      - .offset:         264
        .size:           4
        .value_kind:     hidden_block_count_z
      - .offset:         268
        .size:           2
        .value_kind:     hidden_group_size_x
      - .offset:         270
        .size:           2
        .value_kind:     hidden_group_size_y
      - .offset:         272
        .size:           2
        .value_kind:     hidden_group_size_z
      - .offset:         274
        .size:           2
        .value_kind:     hidden_remainder_x
      - .offset:         276
        .size:           2
        .value_kind:     hidden_remainder_y
      - .offset:         278
        .size:           2
        .value_kind:     hidden_remainder_z
      - .offset:         296
        .size:           8
        .value_kind:     hidden_global_offset_x
      - .offset:         304
        .size:           8
        .value_kind:     hidden_global_offset_y
      - .offset:         312
        .size:           8
        .value_kind:     hidden_global_offset_z
      - .offset:         320
        .size:           2
        .value_kind:     hidden_grid_dims
      - .offset:         344
        .size:           8
        .value_kind:     hidden_multigrid_sync_arg
      - .offset:         376
        .size:           4
        .value_kind:     hidden_dynamic_lds_size
    .group_segment_fixed_size: 0
    .kernarg_segment_align: 8
    .kernarg_segment_size: 512
    .language:       OpenCL C
    .language_version:
      - 2
      - 0
    .max_flat_workgroup_size: 512
    .name:           _Z10hybrid_fwd6Params
    .private_segment_fixed_size: 0
    .sgpr_count:     106
    .sgpr_spill_count: 38
    .symbol:         _Z10hybrid_fwd6Params.kd
    .uniform_work_group_size: 1
    .uses_dynamic_stack: false
    .vgpr_count:     254
    .vgpr_spill_count: 0
    .wavefront_size: 64
